# k14 + dnout and final LayerNorm token mapping made row-block-local so seams 8, 22, 26 also use the 4-workgroup group barrier
# speedup vs baseline: 1.1733x; 1.0054x over previous
; __device__ __forceinline__ unsigned pk2(float lo, float hi) { const f32x2_t v = {lo, hi}; const bf16x2_t b = __builtin_convertvector(v, bf16x2_t); return __builtin_bit_cast(unsigned, b); }
; __device__ __forceinline__ float bflo(unsigned w) { return __uint_as_float(w << 16); }
; __device__ __forceinline__ float bfhi(unsigned w) { return __uint_as_float(w & 0xffff0000u); }
; __device__ __forceinline__ void phase_dnout(ArgsRef a, const Tb tb, int l) {
;     unsigned char* ws = a.ws;
;     const float* OC = (const float*)(ws + OFF_OCRAW); const bf16_t* Z = (const bf16_t*)(ws + OFF_Z); bf16_t* O = (bf16_t*)(ws + OFF_O);
;     const float* g = a.in[11] + l * 128;
;     const int wv = tb.tid >> 6, lane = tb.tid & 63, sub = lane >> 4, l16 = lane & 15;
;     const int gw = tb.bid * 8 + wv, GW = tb.G * 8;
;     const f32x4 g0 = *(const f32x4*)(g + l16 * 8), g1 = *(const f32x4*)(g + l16 * 8 + 4);
;     for (int u = gw * 4 + sub; u < T_ * 4; u += GW * 4) {
;         const int t = u >> 2, h = u & 3;
;         const float* op = OC + (size_t)t * 512 + h * 128 + l16 * 8;
;         const f32x4 v0 = *(const f32x4*)op, v1 = *(const f32x4*)(op + 4);
;         const u32x4 zz = *(const u32x4*)(Z + (size_t)t * 512 + h * 128 + l16 * 8);
;         float ss = (v0[0] * v0[0] + v0[1] * v0[1]) + (v0[2] * v0[2] + v0[3] * v0[3]) + (v1[0] * v1[0] + v1[1] * v1[1]) + (v1[2] * v1[2] + v1[3] * v1[3]);
;         ss += __shfl_xor(ss, 8); ss += __shfl_xor(ss, 4); ss += __shfl_xor(ss, 2); ss += __shfl_xor(ss, 1);
;         const float rn = rsqrtf(ss * (1.f / 128.f) + RMS_EPS_);
;         float o[8];
; #pragma unroll
;         for (int i = 0; i < 4; ++i) {
;             const float za = bflo(zz[i]), zb = bfhi(zz[i]);
;             const float va = i < 2 ? v0[2 * i] : v1[2 * i - 4], vb = i < 2 ? v0[2 * i + 1] : v1[2 * i - 3];
;             const float ga = i < 2 ? g0[2 * i] : g1[2 * i - 4], gb = i < 2 ? g0[2 * i + 1] : g1[2 * i - 3];
;             o[2 * i] = va * rn * ga * (za * __builtin_amdgcn_rcpf(1.f + __expf(-za)));
;             o[2 * i + 1] = vb * rn * gb * (zb * __builtin_amdgcn_rcpf(1.f + __expf(-zb)));
;         }
;         u32x4 w; w[0] = pk2(o[0], o[1]); w[1] = pk2(o[2], o[3]); w[2] = pk2(o[4], o[5]); w[3] = pk2(o[6], o[7]);
;         *(u32x4*)(O + (size_t)t * 1024 + 512 + h * 128 + l16 * 8) = w;
;     }
.LBB0_343:
	s_and_b64 vcc, exec, s[2:3]
	s_cbranch_vccz .LBB0_948
	s_waitcnt vmcnt(0)
	v_ashrrev_i32_e32 v1, 4, v196
	v_and_b32_e32 v1, -4, v1
	v_lshrrev_b32_e32 v0, 4, v196
	s_lshl_b32 s14, s68, 5
	s_mov_b32 s15, 0xffff
	s_cmpk_lg_u32 s56, 0x100
	s_cbranch_scc1 .Ldno_std
	s_and_b32 s14, s68, 7
	s_lshl_b32 s14, s14, 3
	s_bfe_u32 s15, s68, 0x30003
	s_add_i32 s14, s14, s15
	s_lshl_b32 s14, s14, 8
	s_lshr_b32 s15, s68, 6
	s_lshl_b32 s15, s15, 6
	s_add_i32 s14, s14, s15
	s_lshl_b32 s14, s14, 2
	s_add_i32 s15, s14, 0xff
.Ldno_std:
	v_add_u32_e32 v1, s14, v1
	v_and_or_b32 v9, v0, 3, v1
	s_mov_b32 s2, 0x10000
	v_cmp_gt_i32_e32 vcc, s2, v9
	s_and_saveexec_b64 s[2:3], vcc
	s_mov_b32 s13, 0x800000
	s_cbranch_execz .LBB0_347
	v_readlane_b32 s8, v254, 19
	s_waitcnt lgkmcnt(0)
	s_add_u32 s4, s48, 0x9f6a100
	v_readlane_b32 s9, v254, 20
	s_addc_u32 s5, s49, 0
	s_load_dwordx2 s[8:9], s[8:9], 0x58
	s_add_u32 s6, s48, 0xcf6a100
	s_addc_u32 s7, s49, 0
	s_lshl_b32 s10, s50, 7
	s_ashr_i32 s11, s10, 31
	v_lshlrev_b32_e32 v0, 3, v196
	s_lshl_b64 s[10:11], s[10:11], 2
	v_and_b32_e32 v8, 0x78, v0
	s_waitcnt lgkmcnt(0)
	s_add_u32 s8, s8, s10
	s_addc_u32 s9, s9, s11
	v_lshlrev_b32_e32 v4, 2, v8
	global_load_dwordx4 v[0:3], v4, s[8:9]
	s_nop 0
	global_load_dwordx4 v[4:7], v4, s[8:9] offset:16
	v_xor_b32_e32 v10, 8, v236
	v_cmp_lt_i32_e32 vcc, v10, v239
	s_lshl_b32 s10, s56, 5
	s_cmpk_eq_u32 s56, 0x100
	s_cselect_b32 s10, 32, s10
	v_lshlrev_b32_e32 v14, 7, v9
	v_cndmask_b32_e32 v10, v236, v10, vcc
	v_cmp_lt_i32_e32 vcc, v241, v239
	v_lshlrev_b32_e32 v10, 2, v10
	s_lshl_b32 s11, s56, 12
	s_cmpk_eq_u32 s56, 0x100
	s_cselect_b32 s11, 0x1000, s11
	v_cndmask_b32_e32 v11, v236, v241, vcc
	v_cmp_lt_i32_e32 vcc, v240, v239
	v_lshlrev_b32_e32 v11, 2, v11
	s_mov_b64 s[8:9], 0
	v_cndmask_b32_e32 v12, v236, v240, vcc
	v_cmp_lt_i32_e32 vcc, v237, v239
	v_lshlrev_b32_e32 v12, 2, v12
	s_nop 0
	v_cndmask_b32_e32 v13, v236, v237, vcc
	v_lshlrev_b32_e32 v13, 2, v13
.LBB0_346:
	v_ashrrev_i32_e32 v24, 2, v9
	v_ashrrev_i32_e32 v25, 31, v24
	v_lshlrev_b64 v[28:29], 11, v[24:25]
	v_and_b32_e32 v15, 0x180, v14
	v_lshl_add_u64 v[16:17], s[4:5], 0, v[28:29]
	v_lshlrev_b32_e32 v180, 2, v15
	v_lshl_add_u64 v[16:17], v[16:17], 0, v[180:181]
	v_lshlrev_b32_e32 v180, 2, v8
	v_lshl_add_u64 v[20:21], v[16:17], 0, v[180:181]
	global_load_dwordx4 v[16:19], v[20:21], off offset:16
	s_nop 0
	global_load_dwordx4 v[20:23], v[20:21], off
	v_lshlrev_b64 v[24:25], 10, v[24:25]
	v_lshl_add_u64 v[24:25], s[6:7], 0, v[24:25]
	v_lshlrev_b32_e32 v180, 1, v15
	v_lshl_add_u64 v[24:25], v[24:25], 0, v[180:181]
	v_lshlrev_b32_e32 v30, 1, v8
	v_mov_b32_e32 v31, v181
	v_lshl_add_u64 v[24:25], v[24:25], 0, v[30:31]
	global_load_dwordx4 v[24:27], v[24:25], off
	v_add_u32_e32 v9, s10, v9
	s_mov_b32 s12, s15
	v_add_u32_e32 v14, s11, v14
	s_waitcnt vmcnt(1)
	v_pk_mul_f32 v[32:33], v[22:23], v[22:23]
	v_pk_mul_f32 v[34:35], v[20:21], v[20:21]
	s_nop 0
	v_pk_mov_b32 v[36:37], v[34:35], v[32:33] op_sel:[1,0]
	v_mov_b32_e32 v35, v33
	v_pk_add_f32 v[32:33], v[36:37], v[34:35]
	v_pk_mul_f32 v[34:35], v[18:19], v[18:19]
	v_pk_mul_f32 v[36:37], v[16:17], v[16:17]
	v_mov_b32_e32 v38, v34
	v_mov_b32_e32 v39, v36
	v_mov_b32_e32 v36, v35
	v_pk_add_f32 v[34:35], v[38:39], v[36:37]
	v_add_f32_e32 v15, v32, v33
	v_add_f32_e32 v15, v15, v35
	v_add_f32_e32 v15, v34, v15
	ds_bpermute_b32 v32, v10, v15
	s_waitcnt vmcnt(0)
	v_lshlrev_b32_e32 v34, 16, v24
	v_and_b32_e32 v35, 0xffff0000, v24
	v_lshlrev_b32_e32 v24, 16, v25
	v_and_b32_e32 v25, 0xffff0000, v25
	s_waitcnt lgkmcnt(0)
	v_add_f32_e32 v15, v15, v32
	ds_bpermute_b32 v32, v11, v15
	s_waitcnt lgkmcnt(0)
	v_add_f32_e32 v15, v15, v32
	ds_bpermute_b32 v32, v12, v15
	s_waitcnt lgkmcnt(0)
	v_add_f32_e32 v15, v15, v32
	ds_bpermute_b32 v32, v13, v15
	s_waitcnt lgkmcnt(0)
	v_add_f32_e32 v15, v15, v32
	v_fmamk_f32 v15, v15, 0x3c000000, v203
	v_cmp_gt_f32_e32 vcc, s13, v15
	v_mul_f32_e32 v32, 0x4b800000, v15
	s_nop 0
	v_cndmask_b32_e32 v15, v15, v32, vcc
	v_rsq_f32_e32 v15, v15
	s_nop 0
	v_mul_f32_e32 v32, 0x45800000, v15
	v_cndmask_b32_e32 v32, v15, v32, vcc
	v_mul_f32_e32 v15, 0xbfb8aa3b, v34
	v_exp_f32_e32 v15, v15
	v_pk_mul_f32 v[20:21], v[20:21], v[32:33] op_sel_hi:[1,0]
	v_pk_mul_f32 v[22:23], v[22:23], v[32:33] op_sel_hi:[1,0]
	v_pk_mul_f32 v[20:21], v[0:1], v[20:21]
	v_add_f32_e32 v15, 1.0, v15
	v_rcp_f32_e32 v36, v15
	v_mul_f32_e32 v15, 0xbfb8aa3b, v35
	v_exp_f32_e32 v15, v15
	v_pk_mul_f32 v[22:23], v[2:3], v[22:23]
	v_pk_mul_f32 v[16:17], v[16:17], v[32:33] op_sel_hi:[1,0]
	v_pk_mul_f32 v[18:19], v[18:19], v[32:33] op_sel_hi:[1,0]
	v_add_f32_e32 v15, 1.0, v15
	v_rcp_f32_e32 v37, v15
	v_mul_f32_e32 v15, 0xbfb8aa3b, v24
	v_exp_f32_e32 v15, v15
	v_pk_mul_f32 v[16:17], v[4:5], v[16:17]
	v_pk_mul_f32 v[34:35], v[36:37], v[34:35]
	v_pk_mul_f32 v[18:19], v[6:7], v[18:19]
	v_add_f32_e32 v15, 1.0, v15
	v_pk_mul_f32 v[20:21], v[34:35], v[20:21]
	v_rcp_f32_e32 v34, v15
	v_mul_f32_e32 v15, 0xbfb8aa3b, v25
	v_exp_f32_e32 v15, v15
	s_nop 0
	v_add_f32_e32 v15, 1.0, v15
	v_rcp_f32_e32 v35, v15
	s_nop 0
	v_pk_mul_f32 v[24:25], v[34:35], v[24:25]
	s_nop 0
	v_pk_mul_f32 v[22:23], v[24:25], v[22:23]
	v_lshlrev_b32_e32 v24, 16, v26
	v_mul_f32_e32 v15, 0xbfb8aa3b, v24
	v_exp_f32_e32 v15, v15
	v_and_b32_e32 v25, 0xffff0000, v26
	v_add_f32_e32 v15, 1.0, v15
	v_rcp_f32_e32 v34, v15
	v_mul_f32_e32 v15, 0xbfb8aa3b, v25
	v_exp_f32_e32 v15, v15
	s_nop 0
	v_add_f32_e32 v15, 1.0, v15
	v_rcp_f32_e32 v35, v15
	s_nop 0
	v_pk_mul_f32 v[24:25], v[34:35], v[24:25]
	s_nop 0
	v_pk_mul_f32 v[24:25], v[24:25], v[16:17]
	v_lshlrev_b32_e32 v16, 16, v27
	v_mul_f32_e32 v15, 0xbfb8aa3b, v16
	v_exp_f32_e32 v15, v15
	v_and_b32_e32 v17, 0xffff0000, v27
	v_add_f32_e32 v15, 1.0, v15
	v_rcp_f32_e32 v26, v15
	v_mul_f32_e32 v15, 0xbfb8aa3b, v17
	v_exp_f32_e32 v15, v15
	s_nop 0
	v_add_f32_e32 v15, 1.0, v15
	v_rcp_f32_e32 v27, v15
	s_nop 0
	v_pk_mul_f32 v[16:17], v[26:27], v[16:17]
	s_nop 0
	v_pk_mul_f32 v[26:27], v[16:17], v[18:19]
	v_cvt_pk_bf16_f32 v16, v20, v21
	v_lshl_add_u64 v[20:21], s[48:49], 0, v[28:29]
	v_lshl_add_u64 v[20:21], v[20:21], 0, v[180:181]
	v_lshl_add_u64 v[20:21], v[20:21], 0, v[30:31]
	v_add_co_u32_e32 v20, vcc, 0xdf6a000, v20
	v_cvt_pk_bf16_f32 v17, v22, v23
	s_nop 0
	v_addc_co_u32_e32 v21, vcc, 0, v21, vcc
	v_cmp_lt_i32_e32 vcc, s12, v9
	v_cvt_pk_bf16_f32 v18, v24, v25
	v_cvt_pk_bf16_f32 v19, v26, v27
	s_or_b64 s[8:9], vcc, s[8:9]
	global_store_dwordx4 v[20:21], v[16:19], off offset:1280
	s_andn2_b64 exec, exec, s[8:9]
	s_cbranch_execnz .LBB0_346

; __device__ __forceinline__ float bflo(unsigned w) { return __uint_as_float(w << 16); }
; __device__ __forceinline__ float bfhi(unsigned w) { return __uint_as_float(w & 0xffff0000u); }
; __device__ __forceinline__ void phase_final(ArgsRef a, const Tb tb) {
;     const float* part = (const float*)(a.ws + OFF_STATS) + (size_t)5 * T_ * 32;
;     const float* g = a.in[5] + 5 * D_; const float* bb = a.in[6] + 5 * D_;
;     const int wv = tb.tid >> 6, lane = tb.tid & 63;
;     const int gw = tb.bid * 8 + wv, GW = tb.G * 8;
;     for (int t = gw; t < T_; t += GW) {
;         float s = 0.f, q = 0.f;
;         if (lane < 8) { const f32x4 v = *(const f32x4*)(part + (size_t)t * 32 + lane * 4); s = v[0] + v[2]; q = v[1] + v[3]; }
;         s = wave_sum(s); q = wave_sum(q);
;         const float mu = s * (1.f / 1024.f), rstd = rsqrtf(fmaxf(q * (1.f / 1024.f) - mu * mu, 0.f) + LN_EPS_);
; #pragma unroll
;         for (int i = 0; i < 4; ++i) {
;             const int col = i * 256 + lane * 4;
;             const u32x2 rb = *(const u32x2*)((const bf16_t*)(a.ws + OFF_YB) + (size_t)t * D_ + col);
;             f32x4 y = (f32x4){bflo(rb.x), bfhi(rb.x), bflo(rb.y), bfhi(rb.y)};
;             const f32x4 g4 = *(const f32x4*)(g + col), b4 = *(const f32x4*)(bb + col);
.LBB0_1648:
	v_ashrrev_i32_e32 v16, 6, v196
	s_lshl_b32 s8, s68, 3
	s_movk_i32 s18, 0x3fff
	s_cmpk_lg_u32 s56, 0x100
	s_cbranch_scc1 .Lfin_std
	s_and_b32 s8, s68, 7
	s_lshl_b32 s8, s8, 3
	s_bfe_u32 s2, s68, 0x30003
	s_add_i32 s8, s8, s2
	s_lshl_b32 s8, s8, 8
	s_lshr_b32 s2, s68, 6
	s_lshl_b32 s2, s2, 6
	s_add_i32 s8, s8, s2
	s_add_i32 s18, s8, 63
.Lfin_std:
	v_add_u32_e32 v24, s8, v16
	s_movk_i32 s2, 0x4000
	v_cmp_gt_i32_e32 vcc, s2, v24
	s_and_saveexec_b64 s[4:5], vcc
	s_cbranch_execz .LBB0_1653
	v_readlane_b32 s2, v254, 19
	v_readlane_b32 s3, v254, 20
	s_load_dwordx4 s[12:15], s[2:3], 0x28
	s_load_dwordx2 s[16:17], s[2:3], 0x80
	v_cmp_lt_i32_e64 s[2:3], v237, v239
	s_lshl_b32 s6, s56, 3
	s_cmpk_eq_u32 s56, 0x100
	s_cselect_b32 s6, 8, s6
	v_ashrrev_i32_e32 v17, 31, v16
	s_waitcnt vmcnt(0)
	v_cndmask_b32_e64 v0, v236, v237, s[2:3]
	v_cmp_lt_i32_e64 s[2:3], v240, v239
	v_lshlrev_b32_e32 v25, 2, v0
	s_waitcnt lgkmcnt(0)
	s_add_u32 s10, s14, 0x5000
	v_cndmask_b32_e64 v0, v236, v240, s[2:3]
	v_cmp_lt_i32_e64 s[2:3], v241, v239
	v_lshlrev_b32_e32 v26, 2, v0
	s_addc_u32 s11, s15, 0
	v_cndmask_b32_e64 v0, v236, v241, s[2:3]
	v_lshlrev_b32_e32 v27, 2, v0
	v_xor_b32_e32 v0, 8, v236
	v_cmp_lt_i32_e64 s[2:3], v0, v239
	s_add_u32 s12, s12, 0x5000
	s_addc_u32 s13, s13, 0
	v_cndmask_b32_e64 v0, v236, v0, s[2:3]
	v_lshlrev_b32_e32 v28, 2, v0
	v_xor_b32_e32 v0, 16, v236
	v_cmp_lt_i32_e64 s[2:3], v0, v239
	s_ashr_i32 s9, s8, 31
	v_lshl_add_u64 v[20:21], v[16:17], 0, s[8:9]
	v_cndmask_b32_e64 v0, v236, v0, s[2:3]
	v_lshlrev_b32_e32 v29, 2, v0
	v_xor_b32_e32 v0, 32, v236
	v_and_b32_e32 v22, 63, v196
	v_cmp_lt_i32_e64 s[2:3], v0, v239
	v_lshlrev_b64 v[16:17], 7, v[20:21]
	v_lshlrev_b64 v[18:19], 11, v[20:21]
	v_cndmask_b32_e64 v0, v236, v0, s[2:3]
	v_lshlrev_b32_e32 v180, 4, v22
	v_lshl_add_u64 v[16:17], s[48:49], 0, v[16:17]
	s_mov_b64 s[2:3], 0x3425040
	v_lshl_or_b32 v18, v22, 3, v18
	v_or_b32_e32 v6, 0x400, v180
	v_mov_b32_e32 v7, v181
	v_or_b32_e32 v10, 0x800, v180
	v_mov_b32_e32 v11, v181
	v_or_b32_e32 v14, 0xc00, v180
	v_mov_b32_e32 v15, v181
	v_lshl_add_u64 v[16:17], v[16:17], 0, s[2:3]
	s_ashr_i32 s7, s6, 31
	v_lshl_add_u64 v[18:19], s[48:49], 0, v[18:19]
	s_mov_b64 s[2:3], 0x376a500
	v_lshlrev_b64 v[20:21], 12, v[20:21]
	v_cmp_gt_u32_e32 vcc, 8, v22
	v_lshlrev_b32_e32 v30, 2, v0
	v_lshl_add_u64 v[0:1], s[12:13], 0, v[180:181]
	v_lshl_add_u64 v[2:3], s[10:11], 0, v[180:181]
	v_lshl_add_u64 v[4:5], s[12:13], 0, v[6:7]
	v_lshl_add_u64 v[6:7], s[10:11], 0, v[6:7]
	v_lshl_add_u64 v[8:9], s[12:13], 0, v[10:11]
	v_lshl_add_u64 v[10:11], s[10:11], 0, v[10:11]
	v_lshl_add_u64 v[12:13], s[12:13], 0, v[14:15]
	v_lshl_add_u64 v[14:15], s[10:11], 0, v[14:15]
	s_lshl_b64 s[8:9], s[6:7], 7
	v_lshl_add_u64 v[18:19], v[18:19], 0, s[2:3]
	s_lshl_b64 s[10:11], s[6:7], 11
	v_lshl_add_u64 v[20:21], s[16:17], 0, v[20:21]
	s_lshl_b64 s[12:13], s[6:7], 12
	s_mov_b64 s[14:15], 0
	global_load_dwordx4 v[48:51], v[0:1], off
	global_load_dwordx4 v[52:55], v[2:3], off
	global_load_dwordx4 v[56:59], v[4:5], off
	global_load_dwordx4 v[60:63], v[6:7], off
	global_load_dwordx4 v[64:67], v[8:9], off
	global_load_dwordx4 v[68:71], v[10:11], off
	global_load_dwordx4 v[72:75], v[12:13], off
	global_load_dwordx4 v[76:79], v[14:15], off
	s_branch .LBB0_1651
; __device__ __forceinline__ float bflo(unsigned w) { return __uint_as_float(w << 16); }
; __device__ __forceinline__ float bfhi(unsigned w) { return __uint_as_float(w & 0xffff0000u); }
; __device__ __forceinline__ void phase_final(ArgsRef a, const Tb tb) {
;     ...
;     for (int t = gw; t < T_; t += GW) {
;         float s = 0.f, q = 0.f;
;         if (lane < 8) { const f32x4 v = *(const f32x4*)(part + (size_t)t * 32 + lane * 4); s = v[0] + v[2]; q = v[1] + v[3]; }
;         s = wave_sum(s); q = wave_sum(q);
;         const float mu = s * (1.f / 1024.f), rstd = rsqrtf(fmaxf(q * (1.f / 1024.f) - mu * mu, 0.f) + LN_EPS_);
; #pragma unroll
;         for (int i = 0; i < 4; ++i) {
;             const int col = i * 256 + lane * 4;
;             const u32x2 rb = *(const u32x2*)((const bf16_t*)(a.ws + OFF_YB) + (size_t)t * D_ + col);
;             f32x4 y = (f32x4){bflo(rb.x), bfhi(rb.x), bflo(rb.y), bfhi(rb.y)};
;             const f32x4 g4 = *(const f32x4*)(g + col), b4 = *(const f32x4*)(bb + col);
;             y = (y - mu) * rstd * g4 + b4;
;             __builtin_nontemporal_store(y, (f32x4*)(a.out + (size_t)t * D_ + col));
;         }
;     }
.LBB0_1650:
	s_or_b64 exec, exec, s[2:3]
	global_load_dwordx2 v[40:41], v[18:19], off offset:-1024
	global_load_dwordx2 v[42:43], v[18:19], off offset:-512
	global_load_dwordx2 v[44:45], v[18:19], off
	global_load_dwordx2 v[46:47], v[18:19], off offset:512
	s_waitcnt vmcnt(4)
	v_pk_add_f32 v[22:23], v[32:33], v[34:35]
	s_nop 0
	ds_bpermute_b32 v36, v25, v22
	ds_bpermute_b32 v37, v25, v23
	s_waitcnt lgkmcnt(0)
	v_pk_add_f32 v[22:23], v[22:23], v[36:37]
	s_nop 0
	ds_bpermute_b32 v36, v26, v22
	ds_bpermute_b32 v37, v26, v23
	s_waitcnt lgkmcnt(0)
	v_pk_add_f32 v[22:23], v[22:23], v[36:37]
	s_nop 0
	ds_bpermute_b32 v36, v27, v22
	ds_bpermute_b32 v37, v27, v23
	s_waitcnt lgkmcnt(0)
	v_pk_add_f32 v[22:23], v[22:23], v[36:37]
	s_nop 0
	ds_bpermute_b32 v36, v28, v22
	ds_bpermute_b32 v37, v28, v23
	s_waitcnt lgkmcnt(0)
	v_pk_add_f32 v[22:23], v[22:23], v[36:37]
	s_nop 0
	ds_bpermute_b32 v36, v29, v22
	ds_bpermute_b32 v37, v29, v23
	s_waitcnt lgkmcnt(0)
	v_pk_add_f32 v[22:23], v[22:23], v[36:37]
	s_nop 0
	ds_bpermute_b32 v36, v30, v22
	ds_bpermute_b32 v37, v30, v23
	s_waitcnt lgkmcnt(0)
	v_pk_add_f32 v[22:23], v[22:23], v[36:37]
	v_lshl_add_u64 v[38:39], v[20:21], 0, v[180:181]
	v_mul_f32_e32 v22, 0x3a800000, v22
	v_mul_f32_e32 v23, 0x3a800000, v23
	v_fma_f32 v23, -v22, v22, v23
	v_max_f32_e32 v23, 0, v23
	v_add_f32_e32 v23, 0x3727c5ac, v23
	v_rsq_f32_e32 v23, v23
	v_add_u32_e32 v24, s6, v24
	v_lshl_add_u64 v[16:17], v[16:17], 0, s[8:9]
	v_lshl_add_u64 v[18:19], v[18:19], 0, s[10:11]
	v_lshl_add_u64 v[20:21], v[20:21], 0, s[12:13]
	v_cmp_lt_i32_e64 s[2:3], s18, v24
	s_or_b64 s[14:15], s[2:3], s[14:15]
	s_waitcnt vmcnt(0)
	v_lshlrev_b32_e32 v80, 16, v40
	v_and_b32_e32 v81, 0xffff0000, v40
	v_lshlrev_b32_e32 v82, 16, v41
	v_and_b32_e32 v83, 0xffff0000, v41
	v_sub_f32_e32 v80, v80, v22
	v_sub_f32_e32 v81, v81, v22
	v_sub_f32_e32 v82, v82, v22
	v_sub_f32_e32 v83, v83, v22
	v_mul_f32_e32 v80, v80, v23
	v_mul_f32_e32 v81, v81, v23
	v_mul_f32_e32 v82, v82, v23
	v_mul_f32_e32 v83, v83, v23
	v_fma_f32 v80, v48, v80, v52
	v_fma_f32 v81, v49, v81, v53
	v_fma_f32 v82, v50, v82, v54
	v_fma_f32 v83, v51, v83, v55
	global_store_dwordx4 v[38:39], v[80:83], off nt
	v_lshlrev_b32_e32 v84, 16, v42
	v_and_b32_e32 v85, 0xffff0000, v42
	v_lshlrev_b32_e32 v86, 16, v43
	v_and_b32_e32 v87, 0xffff0000, v43
	v_sub_f32_e32 v84, v84, v22
	v_sub_f32_e32 v85, v85, v22
	v_sub_f32_e32 v86, v86, v22
	v_sub_f32_e32 v87, v87, v22
	v_mul_f32_e32 v84, v84, v23
	v_mul_f32_e32 v85, v85, v23
	v_mul_f32_e32 v86, v86, v23
	v_mul_f32_e32 v87, v87, v23
	v_fma_f32 v84, v56, v84, v60
	v_fma_f32 v85, v57, v85, v61
	v_fma_f32 v86, v58, v86, v62
	v_fma_f32 v87, v59, v87, v63
	global_store_dwordx4 v[38:39], v[84:87], off offset:1024 nt
	v_lshlrev_b32_e32 v88, 16, v44
	v_and_b32_e32 v89, 0xffff0000, v44
	v_lshlrev_b32_e32 v90, 16, v45
	v_and_b32_e32 v91, 0xffff0000, v45
	v_sub_f32_e32 v88, v88, v22
	v_sub_f32_e32 v89, v89, v22
	v_sub_f32_e32 v90, v90, v22
	v_sub_f32_e32 v91, v91, v22
	v_mul_f32_e32 v88, v88, v23
	v_mul_f32_e32 v89, v89, v23
	v_mul_f32_e32 v90, v90, v23
	v_mul_f32_e32 v91, v91, v23
	v_fma_f32 v88, v64, v88, v68
	v_fma_f32 v89, v65, v89, v69
	v_fma_f32 v90, v66, v90, v70
	v_fma_f32 v91, v67, v91, v71
	global_store_dwordx4 v[38:39], v[88:91], off offset:2048 nt
	v_lshlrev_b32_e32 v92, 16, v46
	v_and_b32_e32 v93, 0xffff0000, v46
	v_lshlrev_b32_e32 v94, 16, v47
	v_and_b32_e32 v95, 0xffff0000, v47
	v_sub_f32_e32 v92, v92, v22
	v_sub_f32_e32 v93, v93, v22
	v_sub_f32_e32 v94, v94, v22
	v_sub_f32_e32 v95, v95, v22
	v_mul_f32_e32 v92, v92, v23
	v_mul_f32_e32 v93, v93, v23
	v_mul_f32_e32 v94, v94, v23
	v_mul_f32_e32 v95, v95, v23
	v_fma_f32 v92, v72, v92, v76
	v_fma_f32 v93, v73, v93, v77
	v_fma_f32 v94, v74, v94, v78
	v_fma_f32 v95, v75, v95, v79
	global_store_dwordx4 v[38:39], v[92:95], off offset:3072 nt
	s_andn2_b64 exec, exec, s[14:15]
	s_cbranch_execz .LBB0_1653

; __device__ __forceinline__ unsigned xb_ld(unsigned* p)              { return __hip_atomic_load(p, __ATOMIC_RELAXED, __HIP_MEMORY_SCOPE_AGENT); }
; __device__ __forceinline__ unsigned xb_add(unsigned* p, unsigned v) { return __hip_atomic_fetch_add(p, v, __ATOMIC_RELAXED, __HIP_MEMORY_SCOPE_AGENT); }
; #define XB_SPIN(cond, bar) do { unsigned _sp = 0; while (cond) { __builtin_amdgcn_s_sleep(1); \
;     if ((++_sp & 255u) == 0u) { if (xb_ld(&(bar)[XB_TMO])) break; if (_sp > XB_SPIN_CAP) { atomicAdd(&(bar)[XB_TMO], 1u); break; } } } } while (0)
; __device__ __forceinline__ void xcd_barrier(const XcdBarrier& b) {
;     asm volatile("s_waitcnt vmcnt(0)" ::: "memory");
;     __syncthreads();
;     if (threadIdx.x == 0) {
;         unsigned* bar = b.bar;
;         __builtin_amdgcn_s_waitcnt(0);
;         unsigned nloc = b.st[0], nx = b.st[1];
;         if (nloc == 0u) { xcd_barrier_complete(bar, b.x, nloc, nx); b.st[0] = nloc; b.st[1] = nx; }
;         const unsigned old = xb_add(&bar[XB_XSUB(b.x)], 1u);
;         const unsigned gen = old / nloc;
;         if (old + 1u == (gen + 1u) * nloc) {
;             __builtin_amdgcn_fence(__ATOMIC_RELEASE, "agent");
;             asm volatile("s_waitcnt vmcnt(0)" ::: "memory");
;             const unsigned og = xb_add(&bar[XB_TOP], 1u);
;             const unsigned tg = og / nx;
;             if (og + 1u == (tg + 1u) * nx) xb_add(&bar[XB_TOPGEN], 1u);
;             else XB_SPIN(xb_ld(&bar[XB_TOPGEN]) == tg, bar);
;             __builtin_amdgcn_fence(__ATOMIC_ACQUIRE, "agent");
;             xb_add(&bar[XB_XGEN(b.x)], 1u);
;             asm volatile("s_waitcnt vmcnt(0)" ::: "memory");
;         } else {
;             XB_SPIN(xb_ld(&bar[XB_XGEN(b.x)]) == gen, bar);
;             __builtin_amdgcn_fence(__ATOMIC_ACQUIRE, "agent");
;             asm volatile("s_waitcnt vmcnt(0)" ::: "memory");
;         }
;     }
;     __syncthreads();
; }
.LBB0_1655:
	v_readlane_b32 s4, v253, 0
	s_mov_b32 s5, 0x6c19b06
	s_cmpk_lg_u32 s4, 0x100
	s_cbranch_scc1 .Lgb_normal
	s_bitcmp1_b32 s5, s22
	s_cbranch_scc0 .Lgb_normal
	v_readlane_b32 s6, v253, 6
	v_readlane_b32 s7, v253, 7
	v_readlane_b32 s8, v254, 18
	s_and_b32 s9, s8, 7
	s_lshl_b32 s9, s9, 2
	v_mov_b32_e32 v4, s9
	s_and_b32 s8, s8, 63
	s_lshl_b32 s8, s8, 5
	s_addk_i32 s8, 0x3400
	v_mov_b32_e32 v1, s8
	v_mov_b32_e32 v2, 1
	global_load_dword v0, v4, s[6:7] offset:-508 sc1
	s_waitcnt vmcnt(0)
	v_readfirstlane_b32 s9, v0
	s_cmp_eq_u32 s9, 0
	s_cbranch_scc1 .Lgb_normal
	s_add_i32 s10, s9, -1
	s_and_b32 s10, s10, s9
	s_cmp_lg_u32 s10, 0
	s_cbranch_scc1 .Lgb_normal
	global_atomic_add v3, v1, v2, s[6:7] sc0
	s_waitcnt vmcnt(0)
	v_readfirstlane_b32 s9, v3
	s_andn2_b32 s9, s9, 3
	s_add_i32 s9, s9, 4
	s_mov_b32 s11, 0
